# idle-slot filling part 2: phase-10 idle workgroups convert W2B(l), W1A(l+1), WKV(l+1); phase 0 of layers 1..3 converts only W2A + small matrices
# speedup vs baseline: 1.0158x; 1.0087x over previous
; #define PH_BEGIN const int zi = opaque0(); unsigned char* ws = P.ws + zi; float* const OUT = P.out + zi; (void)OUT; const int tid = opqv((int)threadIdx.x); const int bid = opqs((int)blockIdx.x); const int G = opqs((int)gridDim.x); (void)tid; (void)bid; (void)G; unsigned char* WB = ws + WS_WB; float* SS = (float*)(ws + WS_SS); (void)WB; (void)SS; (void)zi;
; __global__ void __launch_bounds__(512) mega(Params P) {
;     ...
;             { PH_BEGIN convT_w<1>(INP(30) + (size_t)l * D * 2 * FF, 2 * FF, 0, INP(29) + (size_t)l * D, (bf16_t*)(WB + WB_W2A), D, D, 2 * FF, bid * 8 + (tid >> 6), G * 8, tid & 63, 4800); }
;             { PH_BEGIN convT_w<0>(INP(31) + (size_t)l * FF * D, D, 0, nullptr, (bf16_t*)(WB + WB_W2B), FF, FF, D, bid * 8 + (tid >> 6), G * 8, tid & 63, 6208); }
;     ...
;         case 10: {
;     ...
;         for (int rep = 0; rep < REPG; ++rep) {
;         { PH_BEGIN
;             pg8::Gemm g{XB_, (const bf16_t*)(WB + WB_W2A), T, 2 * FF, D, D, D, 0, 0}; pg8::StaticOrder S; S.init(T, 2 * FF, G, bid, 1);
;             EpiFFNa E{(bf16_t*)U_, SS + (size_t)2 * T * 16}; pg8::gemm_phase(lds, g, S, E, tid);
;         }
.LBB0_66:
	s_barrier
	s_cmpk_lt_u32 s2, 0x80
	s_cbranch_scc1 .Lp10_noextra
	s_mov_b32 s100, 2
	s_mul_i32 s1, s0, 0xab
	s_bfe_u32 s1, s1, 0x5000b
	s_and_b32 s16, s1, 0xffff
	s_mul_i32 s18, s16, 0x2c0000
	s_mov_b32 s28, 0xc000
	s_mov_b32 s29, 0xe000
	s_mov_b32 s72, 0xd000
	s_mov_b32 s73, 0x9000
	s_movk_i32 s74, 0x7000
	s_sub_i32 s2, s2, 0x80
	s_movk_i32 s3, 0x80
	s_branch .Lp10_tramp_f
.Lp10_back:
	s_mov_b32 s100, 0
	s_mul_i32 s1, s0, 0xab
	s_bfe_u32 s1, s1, 0x5000b
	s_and_b32 s2, s2, 0xffff
	s_add_i32 s2, s2, 0x80
	s_movk_i32 s3, 0x100
.Lp10_noextra:
.LBB0_67:
	s_mov_b64 s[4:5], 0

; #define LAS __attribute__((address_space(3)))
; __device__ __forceinline__ float bflo(unsigned w) { return __uint_as_float(w << 16); }
; __device__ __forceinline__ float bfhi(unsigned w) { return __uint_as_float(w & 0xffff0000u); }
; __device__ __forceinline__ void scan_load_chunk(LAS unsigned char* slot, const float* Wd, const float* V, const bf16_t* RKKB, int p, int rg, int s0, int lt) {
;     ...
;     for (int j = 0; j < 2; ++j) { const int idx = lt + 256 * j, st = idx >> 4, part = idx & 15; *(LAS u32x4*)(slot + st * SCAN_STEP_B + part * 16) = r[j]; }
; #pragma unroll
;     for (int j = 2; j < 6; ++j) { const int k = lt + 256 * (j - 2), st = k >> 5, rem = k & 31, q = rem >> 3, part = rem & 7; const u32x4 w = r[j];
;         const int Q = (q == 0) ? 4 : (q == 1) ? 2 : (q == 2) ? 3 : 1;
;         LAS f32x4* d = (LAS f32x4*)(slot + st * SCAN_STEP_B + Q * 256 + part * 32);
;         d[0] = (f32x4){bflo(w.x), bfhi(w.x), bflo(w.y), bfhi(w.y)}; d[1] = (f32x4){bflo(w.z), bfhi(w.z), bflo(w.w), bfhi(w.w)}; }
;     if (lt < 128) { const int st = lt >> 2, hf = lt & 3; *(LAS u32x4*)(slot + st * SCAN_STEP_B + 1280 + hf * 16) = r[6]; }
.LBB0_368:
	s_or_b64 exec, exec, s[18:19]
	v_add_u32_e32 v14, s23, v80
	v_add3_u32 v0, v14, v0, v76
	s_waitcnt vmcnt(0)
	v_lshlrev_b32_e32 v14, 16, v6
	v_and_b32_e32 v15, 0xffff0000, v6
	v_lshlrev_b32_e32 v16, 16, v7
	v_and_b32_e32 v17, 0xffff0000, v7
	v_lshlrev_b32_e32 v6, 16, v8
	v_and_b32_e32 v7, 0xffff0000, v8
	v_lshlrev_b32_e32 v8, 16, v9
	v_and_b32_e32 v9, 0xffff0000, v9
	ds_write_b128 v0, v[14:17]
	ds_write_b128 v0, v[6:9] offset:16
	s_and_saveexec_b64 s[18:19], s[12:13]
	s_cbranch_execz .LBB0_343
	s_lshr_b32 s20, s23, 15
	s_lshl_b32 s20, s20, 11
	s_add_i32 s20, s20, 0x1f800
	v_and_b32_e32 v14, 0xfc, v232
	v_and_b32_e32 v0, 3, v232
	v_lshl_or_b32 v0, v0, 9, v14
	v_add_u32_e32 v0, s20, v0
	ds_write_b32 v0, v10
	ds_write_b32 v0, v11 offset:128
	ds_write_b32 v0, v12 offset:256
	ds_write_b32 v0, v13 offset:384
	s_branch .LBB0_343
.Lp10_tramp_f:
	s_branch .Lp10_w2b_entry
.Lp10_tramp_b:
	s_branch .Lp10_back
.LBB0_370:
	s_setprio 0
	s_mov_b64 s[4:5], 0

; #define PH_BEGIN const int zi = opaque0(); unsigned char* ws = P.ws + zi; float* const OUT = P.out + zi; (void)OUT; const int tid = opqv((int)threadIdx.x); const int bid = opqs((int)blockIdx.x); const int G = opqs((int)gridDim.x); (void)tid; (void)bid; (void)G; unsigned char* WB = ws + WS_WB; float* SS = (float*)(ws + WS_SS); (void)WB; (void)SS; (void)zi;
; template <int MAP>
; __device__ __forceinline__ void convT_w(const float* src, int ld, int coff, const float* g, bf16_t* dst, int K, int Kd, int Nd, int wslot, int nslots, int lane, int tile_base) {
;     const int nkt = K >> 4, nnt = (Nd + 255) >> 8, ntile = nkt * nnt;
;     for (int t = ((wslot - tile_base) % nslots + nslots) % nslots; t < ntile; t += nslots) {
;         const int kt = t % nkt, ntl = t / nkt, k0 = kt * 16, n = ntl * 256 + lane * 4; const int c = (n < Nd) ? colmap<MAP>(n) : -1;
;         const float* sp = src + (size_t)k0 * ld + coff + (c >= 0 ? c : 0);
; __global__ void __launch_bounds__(512) mega(Params P) {
;     ...
;             { PH_BEGIN convT_w<1>(INP(3) + (size_t)l * D * 2 * FF, 2 * FF, 0, INP(2) + (size_t)l * D, (bf16_t*)(WB + WB_W1A), D, D, 2 * FF, bid * 8 + (tid >> 6), G * 8, tid & 63, 0); }
.LBB0_682:
	s_and_b64 vcc, exec, s[4:5]
	s_cbranch_vccz .LBB0_778
	s_cmp_lg_u32 s96, 0
	s_cbranch_scc1 .LBB0_778
	s_mov_b32 s100, 0
	s_cmp_eq_u32 s1, 0
	s_cbranch_scc1 .Lp10_w1a_entry
	s_or_b32 s2, s2, 0x10000
	s_mov_b32 s3, 0x100000
.Lp10_w1a_entry:
	s_mov_b32 s4, s63
	v_mov_b32_e32 v0, v232
	s_mov_b32 s5, s2
	s_mov_b32 s6, s3
	s_lshl_b32 s18, s6, 3
	s_abs_i32 s6, s18
	v_cvt_f32_u32_e32 v2, s6
	s_waitcnt lgkmcnt(0)
	v_ashrrev_i32_e32 v3, 6, v0
	v_lshl_add_u32 v3, s5, 3, v3
	v_sub_u32_e32 v5, 0, v3
	v_rcp_iflag_f32_e32 v2, v2
	s_sub_i32 s5, 0, s6
	v_ashrrev_i32_e32 v4, 31, v3
	v_max_i32_e32 v3, v3, v5
	v_mul_f32_e32 v2, 0x4f7ffffe, v2
	v_cvt_u32_f32_e32 v2, v2
	s_and_b32 s16, s1, 0xffff
	s_lshl_b32 s19, s16, 10
	s_mul_i32 s17, s16, 0x580000
	v_mul_lo_u32 v5, s5, v2
	v_mul_hi_u32 v5, v2, v5
	v_add_u32_e32 v2, v2, v5
	v_mul_hi_u32 v5, v3, v2
	v_mul_lo_u32 v5, v5, s6
	v_sub_u32_e32 v3, v3, v5
	v_subrev_u32_e32 v5, s6, v3
	v_cmp_le_u32_e32 vcc, s6, v3
	s_movk_i32 s5, 0x580
	s_nop 0
	v_cndmask_b32_e32 v3, v3, v5, vcc
	v_subrev_u32_e32 v5, s6, v3
	v_cmp_le_u32_e32 vcc, s6, v3
	s_nop 1
	v_cndmask_b32_e32 v3, v3, v5, vcc
	v_xor_b32_e32 v3, v3, v4
	v_sub_u32_e32 v3, v3, v4
	v_add_u32_e32 v3, s18, v3
	v_sub_u32_e32 v5, 0, v3
	v_ashrrev_i32_e32 v4, 31, v3
	v_max_i32_e32 v3, v3, v5
	v_mul_hi_u32 v2, v3, v2
	v_mul_lo_u32 v2, v2, s6
	v_sub_u32_e32 v2, v3, v2
	v_subrev_u32_e32 v3, s6, v2
	v_cmp_le_u32_e32 vcc, s6, v2
	s_nop 1
	v_cndmask_b32_e32 v2, v2, v3, vcc
	v_subrev_u32_e32 v3, s6, v2
	v_cmp_le_u32_e32 vcc, s6, v2
	s_nop 1
	v_cndmask_b32_e32 v2, v2, v3, vcc
	v_xor_b32_e32 v2, v2, v4
	v_sub_u32_e32 v31, v2, v4
	v_cmp_gt_i32_e32 vcc, s5, v31
	s_and_saveexec_b64 s[6:7], vcc
	s_mov_b32 s28, 0xc000
	s_mov_b32 s29, 0xe000
	s_mov_b32 s72, 0xd000
	s_mov_b32 s73, 0x9000
	s_movk_i32 s74, 0x7000
	s_cbranch_execz .LBB0_690
	v_readlane_b32 s44, v253, 21
	s_lshl_b32 s5, s17, 2
	v_readlane_b32 s50, v253, 27
	v_readlane_b32 s51, v253, 28
	s_add_u32 s10, s50, s5
	v_readlane_b32 s48, v253, 25
	s_addc_u32 s11, s51, 0
	s_lshl_b32 s5, s19, 2
	v_readlane_b32 s49, v253, 26
	s_add_u32 s12, s48, s5
	s_addc_u32 s13, s49, 0
	s_ashr_i32 s5, s4, 31
	s_add_u32 s8, s92, s4
	s_addc_u32 s9, s93, s5
	s_add_u32 s8, s8, 0x400000
	s_addc_u32 s9, s9, 0
	s_lshl_b64 s[4:5], s[4:5], 2
	s_add_u32 s10, s10, s4
	s_addc_u32 s11, s11, s5
	v_and_b32_e32 v0, 63, v0
	v_readlane_b32 s24, v253, 17
	s_add_u32 s12, s12, s4
	v_lshlrev_b32_e32 v33, 2, v0
	s_mov_b32 s30, 0x3c000
	s_mov_b32 s27, 0x21000
	s_mov_b32 s26, 0x1b000
	v_readlane_b32 s25, v253, 18
	s_addc_u32 s13, s13, s5
	v_cmp_gt_u32_e64 s[4:5], 32, v0
	v_add_u32_e32 v35, 0xa80, v33
	v_lshlrev_b32_e32 v37, 4, v31
	s_lshl_b32 s20, s18, 4
	s_mov_b64 s[14:15], 0
	v_readlane_b32 s45, v253, 22
	v_readlane_b32 s46, v253, 23
	v_readlane_b32 s47, v253, 24
	v_readlane_b32 s52, v253, 29
	v_readlane_b32 s53, v253, 30
	v_readlane_b32 s54, v253, 31
	v_readlane_b32 s55, v253, 32
	v_readlane_b32 s56, v253, 33
	v_readlane_b32 s57, v253, 34
	v_readlane_b32 s58, v253, 35
	v_readlane_b32 s59, v253, 36
	s_branch .LBB0_688

; #define PH_BEGIN const int zi = opaque0(); unsigned char* ws = P.ws + zi; float* const OUT = P.out + zi; (void)OUT; const int tid = opqv((int)threadIdx.x); const int bid = opqs((int)blockIdx.x); const int G = opqs((int)gridDim.x); (void)tid; (void)bid; (void)G; unsigned char* WB = ws + WS_WB; float* SS = (float*)(ws + WS_SS); (void)WB; (void)SS; (void)zi;
; __global__ void __launch_bounds__(512) mega(Params P) {
;     ...
;             { PH_BEGIN convT_w<0>(INP(4) + (size_t)l * FF * D, D, 0, nullptr, (bf16_t*)(WB + WB_W1B), FF, FF, D, bid * 8 + (tid >> 6), G * 8, tid & 63, 1408); }
.LBB0_690:
	s_or_b64 exec, exec, s[6:7]
	s_or_b32 s2, s2, 0x10000
	s_mov_b32 s3, 0x100000

; #define PH_BEGIN const int zi = opaque0(); unsigned char* ws = P.ws + zi; float* const OUT = P.out + zi; (void)OUT; const int tid = opqv((int)threadIdx.x); const int bid = opqs((int)blockIdx.x); const int G = opqs((int)gridDim.x); (void)tid; (void)bid; (void)G; unsigned char* WB = ws + WS_WB; float* SS = (float*)(ws + WS_SS); (void)WB; (void)SS; (void)zi;
; template <int MAP>
; __device__ __forceinline__ void convT_w(const float* src, int ld, int coff, const float* g, bf16_t* dst, int K, int Kd, int Nd, int wslot, int nslots, int lane, int tile_base) {
;     const int nkt = K >> 4, nnt = (Nd + 255) >> 8, ntile = nkt * nnt;
;     for (int t = ((wslot - tile_base) % nslots + nslots) % nslots; t < ntile; t += nslots) {
;         const int kt = t % nkt, ntl = t / nkt, k0 = kt * 16, n = ntl * 256 + lane * 4; const int c = (n < Nd) ? colmap<MAP>(n) : -1;
;         const float* sp = src + (size_t)k0 * ld + coff + (c >= 0 ? c : 0);
; __global__ void __launch_bounds__(512) mega(Params P) {
;     ...
;             { PH_BEGIN convT_w<0>(INP(26) + (size_t)l * D * D, D, 0, INP(6) + (size_t)l * D, (bf16_t*)(WB + WB_WKV), D, D, D, bid * 8 + (tid >> 6), G * 8, tid & 63, 4544); }
.LBB0_720:
	s_or_b64 exec, exec, s[4:5]
	s_cmp_eq_u32 s3, 0x70
	s_cbranch_scc1 .Lp1_back
	s_and_b32 s2, s2, 0xffff
	s_movk_i32 s3, 0x100
	s_cmp_eq_u32 s100, 2
	s_cbranch_scc0 .Lp0_wkv_norm
	s_movk_i32 s3, 0x80
	s_branch .Lp0_wkv_go
.Lp0_wkv_norm:
	s_cmp_eq_u32 s16, 0
	s_cbranch_scc1 .Lp0_wkv_go
	s_or_b32 s2, s2, 0x10000
	s_mov_b32 s3, 0x100000
.Lp0_wkv_go:
	s_mov_b32 s6, s63
	v_mov_b32_e32 v0, v232
	s_mov_b32 s4, s2
	s_mov_b32 s5, s3
	s_lshl_b32 s20, s5, 3
	s_abs_i32 s5, s20
	v_cvt_f32_u32_e32 v2, s5
	v_ashrrev_i32_e32 v3, 6, v0
	v_lshl_add_u32 v3, s4, 3, v3
	v_add_u32_e32 v3, 0xffffee40, v3
	v_rcp_iflag_f32_e32 v2, v2
	v_sub_u32_e32 v5, 0, v3
	s_sub_i32 s4, 0, s5
	v_ashrrev_i32_e32 v4, 31, v3
	v_mul_f32_e32 v2, 0x4f7ffffe, v2
	v_cvt_u32_f32_e32 v2, v2
	v_max_i32_e32 v3, v3, v5
	v_mul_lo_u32 v5, s4, v2
	v_mul_hi_u32 v5, v2, v5
	v_add_u32_e32 v2, v2, v5
	v_mul_hi_u32 v5, v3, v2
	v_mul_lo_u32 v5, v5, s5
	v_sub_u32_e32 v3, v3, v5
	v_subrev_u32_e32 v5, s5, v3
	v_cmp_le_u32_e32 vcc, s5, v3
	s_movk_i32 s4, 0x100
	s_nop 0
	v_cndmask_b32_e32 v3, v3, v5, vcc
	v_subrev_u32_e32 v5, s5, v3
	v_cmp_le_u32_e32 vcc, s5, v3
	s_nop 1
	v_cndmask_b32_e32 v3, v3, v5, vcc
	v_xor_b32_e32 v3, v3, v4
	v_sub_u32_e32 v3, v3, v4
	v_add_u32_e32 v3, s20, v3
	v_sub_u32_e32 v5, 0, v3
	v_ashrrev_i32_e32 v4, 31, v3
	v_max_i32_e32 v3, v3, v5
	v_mul_hi_u32 v2, v3, v2
	v_mul_lo_u32 v2, v2, s5
	v_sub_u32_e32 v2, v3, v2
	v_subrev_u32_e32 v3, s5, v2
	v_cmp_le_u32_e32 vcc, s5, v2
	s_nop 1
	v_cndmask_b32_e32 v2, v2, v3, vcc
	v_subrev_u32_e32 v3, s5, v2
	v_cmp_le_u32_e32 vcc, s5, v2
	s_nop 1
	v_cndmask_b32_e32 v2, v2, v3, vcc
	v_xor_b32_e32 v2, v2, v4
	v_sub_u32_e32 v22, v2, v4
	v_cmp_gt_i32_e32 vcc, s4, v22
	s_and_saveexec_b64 s[4:5], vcc
	s_cbranch_execz .LBB0_727
	v_readlane_b32 s36, v253, 39
	s_lshl_b32 s7, s14, 2
	v_readlane_b32 s40, v253, 43
	v_readlane_b32 s44, v253, 47
	v_readlane_b32 s45, v253, 48
	v_readlane_b32 s46, v253, 49
	v_readlane_b32 s47, v253, 50
	v_readlane_b32 s48, v253, 51
	v_readlane_b32 s49, v253, 52
	v_readlane_b32 s50, v253, 53
	v_readlane_b32 s51, v253, 54
	v_readlane_b32 s41, v253, 44
	s_add_u32 s10, s40, s7
	v_readlane_b32 s44, v253, 21
	s_addc_u32 s11, s41, 0
	v_readlane_b32 s56, v253, 33
	v_readlane_b32 s57, v253, 34
	s_add_u32 s12, s56, s19
	s_addc_u32 s13, s57, 0
	s_ashr_i32 s7, s6, 31
	s_add_u32 s14, s92, s6
	s_addc_u32 s15, s93, s7
	s_lshl_b64 s[8:9], s[6:7], 2
	s_add_u32 s6, s10, s8
	s_addc_u32 s7, s11, s9
	s_add_u32 s8, s12, s8
	s_addc_u32 s9, s13, s9
	v_readlane_b32 s59, v253, 36
	v_readlane_b32 s56, v255, 16
	s_add_u32 s10, s14, 0x2780000
	v_lshlrev_b32_e32 v0, 2, v0
	s_movk_i32 s59, 0x1ff
	v_readlane_b32 s57, v255, 17
	s_addc_u32 s11, s15, 0
	v_and_b32_e32 v23, 0xfc, v0
	v_lshlrev_b32_e32 v24, 4, v22
	s_lshl_b32 s21, s20, 4
	s_mov_b64 s[12:13], 0
	v_readlane_b32 s37, v253, 40
	v_readlane_b32 s38, v253, 41
	v_readlane_b32 s39, v253, 42
	v_readlane_b32 s42, v253, 45
	v_readlane_b32 s43, v253, 46
	v_readlane_b32 s45, v253, 22
	v_readlane_b32 s46, v253, 23
	v_readlane_b32 s47, v253, 24
	v_readlane_b32 s48, v253, 25
	v_readlane_b32 s49, v253, 26
	v_readlane_b32 s50, v253, 27
	v_readlane_b32 s51, v253, 28
	v_readlane_b32 s52, v253, 29
	v_readlane_b32 s53, v253, 30
	v_readlane_b32 s54, v253, 31
	v_readlane_b32 s55, v253, 32
	v_readlane_b32 s58, v253, 35
	s_branch .LBB0_724

; #define PH_BEGIN const int zi = opaque0(); unsigned char* ws = P.ws + zi; float* const OUT = P.out + zi; (void)OUT; const int tid = opqv((int)threadIdx.x); const int bid = opqs((int)blockIdx.x); const int G = opqs((int)gridDim.x); (void)tid; (void)bid; (void)G; unsigned char* WB = ws + WS_WB; float* SS = (float*)(ws + WS_SS); (void)WB; (void)SS; (void)zi;
; template <int MAP>
; __device__ __forceinline__ void convT_w(const float* src, int ld, int coff, const float* g, bf16_t* dst, int K, int Kd, int Nd, int wslot, int nslots, int lane, int tile_base) {
;     const int nkt = K >> 4, nnt = (Nd + 255) >> 8, ntile = nkt * nnt;
;     for (int t = ((wslot - tile_base) % nslots + nslots) % nslots; t < ntile; t += nslots) {
;         const int kt = t % nkt, ntl = t / nkt, k0 = kt * 16, n = ntl * 256 + lane * 4; const int c = (n < Nd) ? colmap<MAP>(n) : -1;
;         const float* sp = src + (size_t)k0 * ld + coff + (c >= 0 ? c : 0);
; __global__ void __launch_bounds__(512) mega(Params P) {
;     ...
;             { PH_BEGIN convT_w<1>(INP(30) + (size_t)l * D * 2 * FF, 2 * FF, 0, INP(29) + (size_t)l * D, (bf16_t*)(WB + WB_W2A), D, D, 2 * FF, bid * 8 + (tid >> 6), G * 8, tid & 63, 4800); }
.LBB0_727:
	s_or_b64 exec, exec, s[4:5]
	s_and_b32 s2, s2, 0xffff
	s_movk_i32 s3, 0x100
	s_cmp_eq_u32 s100, 2
	s_cbranch_scc1 .Lp10_tramp_b
	s_mov_b32 s4, s63
	v_mov_b32_e32 v0, v232
	s_mov_b32 s5, s2
	s_mov_b32 s6, s3
	s_lshl_b32 s20, s6, 3
	s_abs_i32 s6, s20
	s_waitcnt vmcnt(0)
	v_cvt_f32_u32_e32 v2, s6
	v_ashrrev_i32_e32 v3, 6, v0
	v_lshl_add_u32 v3, s5, 3, v3
	v_add_u32_e32 v3, 0xffffed40, v3
	v_rcp_iflag_f32_e32 v2, v2
	v_sub_u32_e32 v5, 0, v3
	s_sub_i32 s5, 0, s6
	v_ashrrev_i32_e32 v4, 31, v3
	v_mul_f32_e32 v2, 0x4f7ffffe, v2
	v_cvt_u32_f32_e32 v2, v2
	v_max_i32_e32 v3, v3, v5
	v_mul_lo_u32 v5, s5, v2
	v_mul_hi_u32 v5, v2, v5
	v_add_u32_e32 v2, v2, v5
	v_mul_hi_u32 v5, v3, v2
	v_mul_lo_u32 v5, v5, s6
	v_sub_u32_e32 v3, v3, v5
	v_subrev_u32_e32 v5, s6, v3
	v_cmp_le_u32_e32 vcc, s6, v3
	s_movk_i32 s5, 0x580
	s_nop 0
	v_cndmask_b32_e32 v3, v3, v5, vcc
	v_subrev_u32_e32 v5, s6, v3
	v_cmp_le_u32_e32 vcc, s6, v3
	s_nop 1
	v_cndmask_b32_e32 v3, v3, v5, vcc
	v_xor_b32_e32 v3, v3, v4
	v_sub_u32_e32 v3, v3, v4
	v_add_u32_e32 v3, s20, v3
	v_sub_u32_e32 v5, 0, v3
	v_ashrrev_i32_e32 v4, 31, v3
	v_max_i32_e32 v3, v3, v5
	v_mul_hi_u32 v2, v3, v2
	v_mul_lo_u32 v2, v2, s6
	v_sub_u32_e32 v2, v3, v2
	v_subrev_u32_e32 v3, s6, v2
	v_cmp_le_u32_e32 vcc, s6, v2
	s_nop 1
	v_cndmask_b32_e32 v2, v2, v3, vcc
	v_subrev_u32_e32 v3, s6, v2
	v_cmp_le_u32_e32 vcc, s6, v2
	s_nop 1
	v_cndmask_b32_e32 v2, v2, v3, vcc
	v_xor_b32_e32 v2, v2, v4
	v_sub_u32_e32 v20, v2, v4
	v_cmp_gt_i32_e32 vcc, s5, v20
	s_and_saveexec_b64 s[6:7], vcc
	s_cbranch_execz .LBB0_733
	v_readlane_b32 s36, v253, 39
	s_lshl_b32 s5, s17, 2
	v_readlane_b32 s48, v253, 51
	v_readlane_b32 s49, v253, 52
	s_add_u32 s8, s48, s5
	v_readlane_b32 s46, v253, 49
	s_addc_u32 s9, s49, 0
	v_readlane_b32 s47, v253, 50
	s_add_u32 s10, s46, s19
	s_addc_u32 s11, s47, 0
	s_ashr_i32 s5, s4, 31
	s_add_u32 s12, s92, s4
	s_addc_u32 s13, s93, s5
	s_lshl_b64 s[4:5], s[4:5], 2
	s_add_u32 s8, s8, s4
	s_addc_u32 s9, s9, s5
	s_add_u32 s10, s10, s4
	s_addc_u32 s11, s11, s5
	v_and_b32_e32 v0, 63, v0
	s_add_u32 s12, s12, 0x2980000
	v_lshlrev_b32_e32 v21, 2, v0
	s_addc_u32 s13, s13, 0
	v_cmp_gt_u32_e64 s[4:5], 32, v0
	v_add_u32_e32 v22, 0xa80, v21
	v_lshlrev_b32_e32 v23, 4, v20
	s_lshl_b32 s17, s20, 4
	s_mov_b64 s[14:15], 0
	v_readlane_b32 s37, v253, 40
	v_readlane_b32 s38, v253, 41
	v_readlane_b32 s39, v253, 42
	v_readlane_b32 s40, v253, 43
	v_readlane_b32 s41, v253, 44
	v_readlane_b32 s42, v253, 45
	v_readlane_b32 s43, v253, 46
	v_readlane_b32 s44, v253, 47
	v_readlane_b32 s45, v253, 48
	v_readlane_b32 s50, v253, 53
	v_readlane_b32 s51, v253, 54
	s_branch .LBB0_731

; #define PH_BEGIN const int zi = opaque0(); unsigned char* ws = P.ws + zi; float* const OUT = P.out + zi; (void)OUT; const int tid = opqv((int)threadIdx.x); const int bid = opqs((int)blockIdx.x); const int G = opqs((int)gridDim.x); (void)tid; (void)bid; (void)G; unsigned char* WB = ws + WS_WB; float* SS = (float*)(ws + WS_SS); (void)WB; (void)SS; (void)zi;
; template <int MAP>
; __device__ __forceinline__ void convT_w(const float* src, int ld, int coff, const float* g, bf16_t* dst, int K, int Kd, int Nd, int wslot, int nslots, int lane, int tile_base) {
;     const int nkt = K >> 4, nnt = (Nd + 255) >> 8, ntile = nkt * nnt;
;     for (int t = ((wslot - tile_base) % nslots + nslots) % nslots; t < ntile; t += nslots) {
;         const int kt = t % nkt, ntl = t / nkt, k0 = kt * 16, n = ntl * 256 + lane * 4; const int c = (n < Nd) ? colmap<MAP>(n) : -1;
;         const float* sp = src + (size_t)k0 * ld + coff + (c >= 0 ? c : 0);
; __global__ void __launch_bounds__(512) mega(Params P) {
;     ...
;             { PH_BEGIN convT_w<0>(INP(31) + (size_t)l * FF * D, D, 0, nullptr, (bf16_t*)(WB + WB_W2B), FF, FF, D, bid * 8 + (tid >> 6), G * 8, tid & 63, 6208); }
.Lp10_w2b_entry:
	s_mov_b32 s6, s63
	v_mov_b32_e32 v0, v232
	s_mov_b32 s4, s2
	s_mov_b32 s5, s3
	s_lshl_b32 s14, s5, 3
	s_abs_i32 s5, s14
	v_cvt_f32_u32_e32 v2, s5
	v_ashrrev_i32_e32 v3, 6, v0
	v_lshl_add_u32 v3, s4, 3, v3
	v_add_u32_e32 v3, 0xffffe7c0, v3
	v_rcp_iflag_f32_e32 v2, v2
	v_sub_u32_e32 v5, 0, v3
	s_sub_i32 s4, 0, s5
	v_ashrrev_i32_e32 v4, 31, v3
	v_mul_f32_e32 v2, 0x4f7ffffe, v2
	v_cvt_u32_f32_e32 v2, v2
	v_max_i32_e32 v3, v3, v5
	v_mul_lo_u32 v5, s4, v2
	v_mul_hi_u32 v5, v2, v5
	v_add_u32_e32 v2, v2, v5
	v_mul_hi_u32 v5, v3, v2
	v_mul_lo_u32 v5, v5, s5
	v_sub_u32_e32 v3, v3, v5
	v_subrev_u32_e32 v5, s5, v3
	v_cmp_le_u32_e32 vcc, s5, v3
	s_movk_i32 s4, 0x2c0
	s_nop 0
	v_cndmask_b32_e32 v3, v3, v5, vcc
	v_subrev_u32_e32 v5, s5, v3
	v_cmp_le_u32_e32 vcc, s5, v3
	s_nop 1
	v_cndmask_b32_e32 v3, v3, v5, vcc
	v_xor_b32_e32 v3, v3, v4
	v_sub_u32_e32 v3, v3, v4
	v_add_u32_e32 v3, s14, v3
	v_sub_u32_e32 v5, 0, v3
	v_ashrrev_i32_e32 v4, 31, v3
	v_max_i32_e32 v3, v3, v5
	v_mul_hi_u32 v2, v3, v2
	v_mul_lo_u32 v2, v2, s5
	v_sub_u32_e32 v2, v3, v2
	v_subrev_u32_e32 v3, s5, v2
	v_cmp_le_u32_e32 vcc, s5, v2
	s_nop 1
	v_cndmask_b32_e32 v2, v2, v3, vcc
	v_subrev_u32_e32 v3, s5, v2
	v_cmp_le_u32_e32 vcc, s5, v2
	s_nop 1
	v_cndmask_b32_e32 v2, v2, v3, vcc
	v_xor_b32_e32 v2, v2, v4
	v_sub_u32_e32 v3, v2, v4
	v_cmp_gt_i32_e32 vcc, s4, v3
	s_and_saveexec_b64 s[4:5], vcc
	s_cbranch_execz .LBB0_738
	v_readlane_b32 s36, v253, 39
	s_lshl_b32 s7, s18, 2
	v_readlane_b32 s50, v253, 53
	v_readlane_b32 s51, v253, 54
	s_add_u32 s8, s50, s7
	s_addc_u32 s9, s51, 0
	s_ashr_i32 s7, s6, 31
	s_add_u32 s10, s92, s6
	s_addc_u32 s11, s93, s7
	s_lshl_b64 s[6:7], s[6:7], 2
	s_add_u32 s6, s8, s6
	s_addc_u32 s7, s9, s7
	s_add_u32 s8, s10, 0x3480000
	v_lshlrev_b32_e32 v0, 2, v0
	s_addc_u32 s9, s11, 0
	v_and_b32_e32 v4, 0xfc, v0
	v_lshlrev_b32_e32 v2, 4, v3
	s_lshl_b32 s15, s14, 4
	s_mov_b64 s[10:11], 0
	v_readlane_b32 s37, v253, 40
	v_readlane_b32 s38, v253, 41
	v_readlane_b32 s39, v253, 42
	v_readlane_b32 s40, v253, 43
	v_readlane_b32 s41, v253, 44
	v_readlane_b32 s42, v253, 45
	v_readlane_b32 s43, v253, 46
	v_readlane_b32 s44, v253, 47
	v_readlane_b32 s45, v253, 48
	v_readlane_b32 s46, v253, 49
	v_readlane_b32 s47, v253, 50
	v_readlane_b32 s48, v253, 51
	v_readlane_b32 s49, v253, 52
	s_branch .LBB0_736

; #define PH_BEGIN const int zi = opaque0(); unsigned char* ws = P.ws + zi; float* const OUT = P.out + zi; (void)OUT; const int tid = opqv((int)threadIdx.x); const int bid = opqs((int)blockIdx.x); const int G = opqs((int)gridDim.x); (void)tid; (void)bid; (void)G; unsigned char* WB = ws + WS_WB; float* SS = (float*)(ws + WS_SS); (void)WB; (void)SS; (void)zi;
; __global__ void __launch_bounds__(512) mega(Params P) {
;     ...
;             { PH_BEGIN convT_w<0>(INP(31) + (size_t)l * FF * D, D, 0, nullptr, (bf16_t*)(WB + WB_W2B), FF, FF, D, bid * 8 + (tid >> 6), G * 8, tid & 63, 6208); }
;             { PH_BEGIN convT_w<0>(INP(10) + (size_t)l * 64 * 512, 512, 0, nullptr, (bf16_t*)(WB + WB_LW2), 64, 64, 512, bid * 8 + (tid >> 6), G * 8, tid & 63, 6912); }
;             { PH_BEGIN convT_w<0>(INP(12) + (size_t)l * 64 * 512, 512, 0, nullptr, (bf16_t*)(WB + WB_LA2), 64, 64, 512, bid * 8 + (tid >> 6), G * 8, tid & 63, 6920); }
;             { PH_BEGIN convT_w<0>(INP(13) + (size_t)l * 128 * 512, 512, 0, nullptr, (bf16_t*)(WB + WB_LG2), 128, 128, 512, bid * 8 + (tid >> 6), G * 8, tid & 63, 6928); }
.LBB0_738:
	s_or_b64 exec, exec, s[4:5]
	s_cmp_eq_u32 s100, 2
	s_cbranch_scc0 .Lp0_w2b_norm
	s_cmp_eq_u32 s1, 3
	s_cbranch_scc1 .Lp10_tramp_b
	s_add_i32 s1, s1, 1
	s_branch .Lp10_w1a_entry
.Lp0_w2b_norm:
	s_and_b32 s2, s2, 0xffff
	s_movk_i32 s3, 0x100
	s_mov_b32 s6, s63
	v_mov_b32_e32 v0, v232
	s_mov_b32 s4, s2
	s_mov_b32 s5, s3
	s_lshl_b32 s15, s5, 3
	s_abs_i32 s5, s15
	v_cvt_f32_u32_e32 v2, s5
	v_ashrrev_i32_e32 v3, 6, v0
	v_lshl_add_u32 v3, s4, 3, v3
	v_add_u32_e32 v3, 0xffffe500, v3
	v_rcp_iflag_f32_e32 v2, v2
	v_sub_u32_e32 v5, 0, v3
	s_sub_i32 s4, 0, s5
	v_ashrrev_i32_e32 v4, 31, v3
	v_mul_f32_e32 v2, 0x4f7ffffe, v2
	v_cvt_u32_f32_e32 v2, v2
	v_max_i32_e32 v3, v3, v5
	s_lshl_b32 s14, s16, 15
	v_mul_lo_u32 v5, s4, v2
	v_mul_hi_u32 v5, v2, v5
	v_add_u32_e32 v2, v2, v5
	v_mul_hi_u32 v5, v3, v2
	v_mul_lo_u32 v5, v5, s5
	v_sub_u32_e32 v3, v3, v5
	v_subrev_u32_e32 v5, s5, v3
	v_cmp_le_u32_e32 vcc, s5, v3
	s_nop 1
	v_cndmask_b32_e32 v3, v3, v5, vcc
	v_subrev_u32_e32 v5, s5, v3
	v_cmp_le_u32_e32 vcc, s5, v3
	s_nop 1
	v_cndmask_b32_e32 v3, v3, v5, vcc
	v_xor_b32_e32 v3, v3, v4
	v_sub_u32_e32 v3, v3, v4
	v_add_u32_e32 v3, s15, v3
	v_sub_u32_e32 v5, 0, v3
	v_ashrrev_i32_e32 v4, 31, v3
	v_max_i32_e32 v3, v3, v5
	v_mul_hi_u32 v2, v3, v2
	v_mul_lo_u32 v2, v2, s5
	v_sub_u32_e32 v2, v3, v2
	v_subrev_u32_e32 v3, s5, v2
	v_cmp_le_u32_e32 vcc, s5, v2
	s_nop 1
	v_cndmask_b32_e32 v2, v2, v3, vcc
	v_subrev_u32_e32 v3, s5, v2
	v_cmp_le_u32_e32 vcc, s5, v2
	s_nop 1
	v_cndmask_b32_e32 v2, v2, v3, vcc
	v_xor_b32_e32 v2, v2, v4
	v_sub_u32_e32 v4, v2, v4
	v_cmp_gt_i32_e32 vcc, 8, v4
	s_and_saveexec_b64 s[4:5], vcc
	s_cbranch_execz .LBB0_743
	v_readlane_b32 s36, v252, 8
	s_lshl_b32 s7, s14, 2
	v_readlane_b32 s40, v252, 12
	v_readlane_b32 s41, v252, 13
	s_add_u32 s8, s40, s7
	s_addc_u32 s9, s41, 0
	s_ashr_i32 s7, s6, 31
	s_add_u32 s10, s92, s6
	s_addc_u32 s11, s93, s7
	s_lshl_b64 s[6:7], s[6:7], 2
	s_add_u32 s6, s8, s6
	s_addc_u32 s7, s9, s7
	s_add_u32 s8, s10, 0x3a00000
	v_lshlrev_b32_e32 v0, 2, v0
	s_addc_u32 s9, s11, 0
	v_and_b32_e32 v5, 0xfc, v0
	v_lshlrev_b32_e32 v6, 4, v4
	s_lshl_b32 s17, s15, 4
	s_mov_b64 s[10:11], 0
	v_readlane_b32 s37, v252, 9
	v_readlane_b32 s38, v252, 10
	v_readlane_b32 s39, v252, 11
	v_readlane_b32 s42, v252, 14
	v_readlane_b32 s43, v252, 15
	v_readlane_b32 s44, v252, 16
	v_readlane_b32 s45, v252, 17
	v_readlane_b32 s46, v252, 18
	v_readlane_b32 s47, v252, 19
	v_readlane_b32 s48, v252, 20
	v_readlane_b32 s49, v252, 21
	v_readlane_b32 s50, v252, 22
	v_readlane_b32 s51, v252, 23
	s_branch .LBB0_741

; __global__ void __launch_bounds__(512) mega(Params P) {
	.amdhsa_kernel _Z4mega6Params
		.amdhsa_group_segment_fixed_size 0
		.amdhsa_private_segment_fixed_size 0
		.amdhsa_kernarg_size 536
		.amdhsa_user_sgpr_count 2
		.amdhsa_user_sgpr_dispatch_ptr 0
		.amdhsa_user_sgpr_queue_ptr 0
		.amdhsa_user_sgpr_kernarg_segment_ptr 1
		.amdhsa_user_sgpr_dispatch_id 0
		.amdhsa_user_sgpr_kernarg_preload_length 0
		.amdhsa_user_sgpr_kernarg_preload_offset 0
		.amdhsa_user_sgpr_private_segment_size 0
		.amdhsa_uses_dynamic_stack 0
		.amdhsa_enable_private_segment 0
		.amdhsa_system_sgpr_workgroup_id_x 1
		.amdhsa_system_sgpr_workgroup_id_y 0
		.amdhsa_system_sgpr_workgroup_id_z 0
		.amdhsa_system_sgpr_workgroup_info 0
		.amdhsa_system_vgpr_workitem_id 2
		.amdhsa_next_free_vgpr 256
		.amdhsa_next_free_sgpr 102
		.amdhsa_accum_offset 256
		.amdhsa_reserve_vcc 1
		.amdhsa_float_round_mode_32 0
		.amdhsa_float_round_mode_16_64 0
		.amdhsa_float_denorm_mode_32 3
		.amdhsa_float_denorm_mode_16_64 3
		.amdhsa_dx10_clamp 1
		.amdhsa_ieee_mode 1
		.amdhsa_fp16_overflow 0
		.amdhsa_tg_split 0
		.amdhsa_exception_fp_ieee_invalid_op 0
		.amdhsa_exception_fp_denorm_src 0
		.amdhsa_exception_fp_ieee_div_zero 0
		.amdhsa_exception_fp_ieee_overflow 0
		.amdhsa_exception_fp_ieee_underflow 0
		.amdhsa_exception_fp_ieee_inexact 0
		.amdhsa_exception_int_div_zero 0
	.end_amdhsa_kernel

; __global__ void __launch_bounds__(512) mega(Params P) {
amdhsa.kernels:
  - .agpr_count:     0
    .args:
      - .offset:         0
        .size:           280
        .value_kind:     by_value
      - .offset:         280
        .size:           4
        .value_kind:     hidden_block_count_x
      - .offset:         284
        .size:           4
        .value_kind:     hidden_block_count_y
      - .offset:         288
        .size:           4
        .value_kind:     hidden_block_count_z
      - .offset:         292
        .size:           2
        .value_kind:     hidden_group_size_x
      - .offset:         294
        .size:           2
        .value_kind:     hidden_group_size_y
      - .offset:         296
        .size:           2
        .value_kind:     hidden_group_size_z
      - .offset:         298
        .size:           2
        .value_kind:     hidden_remainder_x
      - .offset:         300
        .size:           2
        .value_kind:     hidden_remainder_y
      - .offset:         302
        .size:           2
        .value_kind:     hidden_remainder_z
      - .offset:         320
        .size:           8
        .value_kind:     hidden_global_offset_x
      - .offset:         328
        .size:           8
        .value_kind:     hidden_global_offset_y
      - .offset:         336
        .size:           8
        .value_kind:     hidden_global_offset_z
      - .offset:         344
        .size:           2
        .value_kind:     hidden_grid_dims
      - .offset:         368
        .size:           8
        .value_kind:     hidden_multigrid_sync_arg
      - .offset:         400
        .size:           4
        .value_kind:     hidden_dynamic_lds_size
    .group_segment_fixed_size: 0
    .kernarg_segment_align: 8
    .kernarg_segment_size: 536
    .language:       OpenCL C
    .language_version:
      - 2
      - 0
    .max_flat_workgroup_size: 512
    .name:           _Z4mega6Params
    .private_segment_fixed_size: 0
    .sgpr_count:     108
    .sgpr_spill_count: 210
    .symbol:         _Z4mega6Params.kd
    .uniform_work_group_size: 1
    .uses_dynamic_stack: false
    .vgpr_count:     256
    .vgpr_spill_count: 0
    .wavefront_size: 64
